# nt policy also on the once-read f32 weight loads of the P6 side conversion (mla_out/up1/dn1)
# speedup vs baseline: 1.0109x; 1.0067x over previous
.LBB0_963:
	s_cmpk_gt_i32 s3, 0x1ff
	s_mov_b64 s[14:15], -1
	s_cbranch_scc0 .LBB0_969
	s_cmpk_gt_u32 s3, 0x9ff
	s_cbranch_scc0 .LBB0_966
	s_and_b32 s8, s5, 0x7fffffc0
	s_and_b32 s14, s4, 0x3e0
	v_or_b32_e32 v2, s8, v12
	v_or_b32_e32 v28, s14, v1
	v_lshlrev_b64 v[26:27], 12, v[2:3]
	v_lshl_add_u64 v[26:27], s[10:11], 0, v[26:27]
	v_lshlrev_b32_e32 v2, 2, v28
	v_lshl_add_u64 v[26:27], v[26:27], 0, v[2:3]
	v_add_co_u32_e32 v28, vcc, 0x2000, v26
	s_lshl_b32 s8, s8, 1
	s_nop 0
	v_addc_co_u32_e32 v29, vcc, 0, v27, vcc
	v_add_co_u32_e32 v30, vcc, 0x4000, v26
	s_nop 1
	v_addc_co_u32_e32 v31, vcc, 0, v27, vcc
	v_add_co_u32_e32 v32, vcc, 0x6000, v26
	s_nop 1
	v_addc_co_u32_e32 v33, vcc, 0, v27, vcc
	v_add_co_u32_e32 v34, vcc, 0x8000, v26
	s_nop 1
	v_addc_co_u32_e32 v35, vcc, 0, v27, vcc
	v_add_co_u32_e32 v36, vcc, 0xa000, v26
	s_nop 1
	v_addc_co_u32_e32 v37, vcc, 0, v27, vcc
	v_add_co_u32_e32 v38, vcc, 0xc000, v26
	s_nop 1
	v_addc_co_u32_e32 v39, vcc, 0, v27, vcc
	v_add_co_u32_e32 v40, vcc, 0xe000, v26
	s_nop 1
	v_addc_co_u32_e32 v41, vcc, 0, v27, vcc
	global_load_dword v2, v[26:27], off nt
	global_load_dword v44, v[28:29], off nt
	global_load_dword v45, v[30:31], off nt
	global_load_dword v46, v[32:33], off nt
	global_load_dword v47, v[34:35], off nt
	global_load_dword v48, v[36:37], off nt
	global_load_dword v49, v[38:39], off nt
	global_load_dword v50, v[40:41], off nt
	v_add_co_u32_e32 v28, vcc, 0x10000, v26
	s_nop 1
	v_addc_co_u32_e32 v29, vcc, 0, v27, vcc
	v_add_co_u32_e32 v30, vcc, 0x12000, v26
	s_nop 1
	v_addc_co_u32_e32 v31, vcc, 0, v27, vcc
	v_add_co_u32_e32 v32, vcc, 0x14000, v26
	s_nop 1
	v_addc_co_u32_e32 v33, vcc, 0, v27, vcc
	v_add_co_u32_e32 v34, vcc, 0x16000, v26
	s_nop 1
	v_addc_co_u32_e32 v35, vcc, 0, v27, vcc
	v_add_co_u32_e32 v36, vcc, 0x18000, v26
	s_nop 1
	v_addc_co_u32_e32 v37, vcc, 0, v27, vcc
	v_add_co_u32_e32 v38, vcc, 0x1a000, v26
	s_nop 1
	v_addc_co_u32_e32 v39, vcc, 0, v27, vcc
	v_add_co_u32_e32 v40, vcc, 0x1c000, v26
	s_nop 1
	v_addc_co_u32_e32 v41, vcc, 0, v27, vcc
	v_add_co_u32_e32 v42, vcc, 0x1e000, v26
	s_nop 1
	v_addc_co_u32_e32 v43, vcc, 0, v27, vcc
	global_load_dword v51, v[28:29], off nt
	global_load_dword v52, v[30:31], off nt
	global_load_dword v53, v[32:33], off nt
	global_load_dword v54, v[34:35], off nt
	global_load_dword v55, v[36:37], off nt
	global_load_dword v56, v[38:39], off nt
	global_load_dword v57, v[40:41], off nt
	global_load_dword v58, v[42:43], off nt
	v_add_co_u32_e32 v28, vcc, 0x20000, v26
	s_nop 1
	v_addc_co_u32_e32 v29, vcc, 0, v27, vcc
	v_add_co_u32_e32 v30, vcc, 0x22000, v26
	s_nop 1
	v_addc_co_u32_e32 v31, vcc, 0, v27, vcc
	v_add_co_u32_e32 v32, vcc, 0x24000, v26
	s_nop 1
	v_addc_co_u32_e32 v33, vcc, 0, v27, vcc
	v_add_co_u32_e32 v34, vcc, 0x26000, v26
	s_nop 1
	v_addc_co_u32_e32 v35, vcc, 0, v27, vcc
	v_add_co_u32_e32 v36, vcc, 0x28000, v26
	s_nop 1
	v_addc_co_u32_e32 v37, vcc, 0, v27, vcc
	v_add_co_u32_e32 v38, vcc, 0x2a000, v26
	s_nop 1
	v_addc_co_u32_e32 v39, vcc, 0, v27, vcc
	v_add_co_u32_e32 v40, vcc, 0x2c000, v26
	s_nop 1
	v_addc_co_u32_e32 v41, vcc, 0, v27, vcc
	v_add_co_u32_e32 v42, vcc, 0x2e000, v26
	s_nop 1
	v_addc_co_u32_e32 v43, vcc, 0, v27, vcc
	global_load_dword v59, v[28:29], off nt
	global_load_dword v60, v[30:31], off nt
	global_load_dword v61, v[32:33], off nt
	global_load_dword v62, v[34:35], off nt
	global_load_dword v63, v[36:37], off nt
	global_load_dword v64, v[38:39], off nt
	global_load_dword v65, v[40:41], off nt
	s_nop 0
	global_load_dword v42, v[42:43], off nt
	v_add_co_u32_e32 v28, vcc, 0x30000, v26
	s_nop 1
	v_addc_co_u32_e32 v29, vcc, 0, v27, vcc
	v_add_co_u32_e32 v30, vcc, 0x32000, v26
	s_nop 1
	v_addc_co_u32_e32 v31, vcc, 0, v27, vcc
	v_add_co_u32_e32 v32, vcc, 0x34000, v26
	s_nop 1
	v_addc_co_u32_e32 v33, vcc, 0, v27, vcc
	v_add_co_u32_e32 v34, vcc, 0x36000, v26
	s_nop 1
	v_addc_co_u32_e32 v35, vcc, 0, v27, vcc
	v_add_co_u32_e32 v36, vcc, 0x38000, v26
	s_nop 1
	v_addc_co_u32_e32 v37, vcc, 0, v27, vcc
	v_add_co_u32_e32 v38, vcc, 0x3a000, v26
	s_nop 1
	v_addc_co_u32_e32 v39, vcc, 0, v27, vcc
	v_add_co_u32_e32 v40, vcc, 0x3c000, v26
	s_nop 1
	v_addc_co_u32_e32 v41, vcc, 0, v27, vcc
	v_add_co_u32_e32 v26, vcc, 0x3e000, v26
	s_nop 1
	v_addc_co_u32_e32 v27, vcc, 0, v27, vcc
	global_load_dword v28, v[28:29], off nt
	s_nop 0
	global_load_dword v29, v[30:31], off nt
	s_nop 0
	global_load_dword v30, v[32:33], off nt
	global_load_dword v31, v[34:35], off nt
	s_nop 0
	global_load_dword v32, v[36:37], off nt
	global_load_dword v33, v[38:39], off nt
	global_load_dword v34, v[40:41], off nt
	s_nop 0
	global_load_dword v26, v[26:27], off nt
	s_waitcnt vmcnt(30)
	ds_write2_b32 v13, v2, v44 offset1:66
	s_waitcnt vmcnt(28)
	ds_write2_b32 v13, v45, v46 offset0:132 offset1:198
	s_waitcnt vmcnt(26)
	ds_write2_b32 v19, v47, v48 offset0:8 offset1:74
	s_waitcnt vmcnt(24)
	ds_write2_b32 v19, v49, v50 offset0:140 offset1:206
	s_waitcnt vmcnt(22)
	ds_write2_b32 v20, v51, v52 offset0:16 offset1:82
	s_waitcnt vmcnt(20)
	ds_write2_b32 v20, v53, v54 offset0:148 offset1:214
	s_waitcnt vmcnt(18)
	ds_write2_b32 v21, v55, v56 offset0:24 offset1:90
	s_waitcnt vmcnt(16)
	ds_write2_b32 v21, v57, v58 offset0:156 offset1:222
	s_waitcnt vmcnt(14)
	ds_write2_b32 v22, v59, v60 offset0:32 offset1:98
	s_waitcnt vmcnt(12)
	ds_write2_b32 v22, v61, v62 offset0:164 offset1:230
	s_waitcnt vmcnt(10)
	ds_write2_b32 v23, v63, v64 offset0:40 offset1:106
	s_waitcnt vmcnt(8)
	ds_write2_b32 v23, v65, v42 offset0:172 offset1:238
	s_waitcnt vmcnt(6)
	ds_write2_b32 v24, v28, v29 offset0:48 offset1:114
	s_waitcnt vmcnt(4)
	ds_write2_b32 v24, v30, v31 offset0:180 offset1:246
	s_waitcnt vmcnt(2)
	ds_write2_b32 v25, v32, v33 offset0:56 offset1:122
	s_waitcnt vmcnt(0)
	ds_write2_b32 v25, v34, v26 offset0:188 offset1:254
	s_waitcnt lgkmcnt(0)
	ds_read2_b32 v[30:31], v15 offset1:8
	ds_read2_b32 v[34:35], v15 offset0:33 offset1:41
	ds_read2_b32 v[36:37], v15 offset0:66 offset1:74
	ds_read2_b32 v[38:39], v15 offset0:99 offset1:107
	ds_read2_b32 v[40:41], v15 offset0:132 offset1:140
	s_waitcnt lgkmcnt(4)
	v_bfe_u32 v2, v30, 16, 1
	v_add3_u32 v2, v30, v2, s52
	s_waitcnt lgkmcnt(3)
	v_bfe_u32 v26, v34, 16, 1
	v_lshrrev_b32_e32 v2, 16, v2
	v_add3_u32 v26, v34, v26, s52
	ds_read2_b32 v[42:43], v15 offset0:165 offset1:173
	v_and_or_b32 v26, v26, s53, v2
	s_waitcnt lgkmcnt(3)
	v_bfe_u32 v2, v36, 16, 1
	v_add3_u32 v2, v36, v2, s52
	s_waitcnt lgkmcnt(2)
	v_bfe_u32 v27, v38, 16, 1
	ds_read2_b32 v[44:45], v15 offset0:198 offset1:206
	v_lshrrev_b32_e32 v2, 16, v2
	v_add3_u32 v27, v38, v27, s52
	ds_read2_b32 v[46:47], v15 offset0:231 offset1:239
	v_and_or_b32 v27, v27, s53, v2
	s_waitcnt lgkmcnt(3)
	v_bfe_u32 v2, v40, 16, 1
	v_add3_u32 v2, v40, v2, s52
	s_waitcnt lgkmcnt(2)
	v_bfe_u32 v28, v42, 16, 1
	v_lshrrev_b32_e32 v2, 16, v2
	v_add3_u32 v28, v42, v28, s52
	v_and_or_b32 v28, v28, s53, v2
	s_waitcnt lgkmcnt(1)
	v_bfe_u32 v2, v44, 16, 1
	v_add3_u32 v2, v44, v2, s52
	s_waitcnt lgkmcnt(0)
	v_bfe_u32 v29, v46, 16, 1
	v_lshrrev_b32_e32 v2, 16, v2
	v_add3_u32 v29, v46, v29, s52
	v_and_or_b32 v29, v29, s53, v2
	v_or_b32_e32 v2, s14, v14
	v_lshl_add_u64 v[32:33], v[4:5], 0, s[8:9]
	v_lshlrev_b32_e32 v2, 13, v2
	v_lshl_add_u64 v[48:49], v[32:33], 0, v[2:3]
	v_bfe_u32 v2, v31, 16, 1
	global_store_dwordx4 v[48:49], v[26:29], off
	v_add3_u32 v2, v31, v2, s52
	v_lshrrev_b32_e32 v2, 16, v2
	v_bfe_u32 v26, v35, 16, 1
	v_add3_u32 v26, v35, v26, s52
	v_and_or_b32 v26, v26, s53, v2
	v_bfe_u32 v2, v37, 16, 1
	v_add3_u32 v2, v37, v2, s52
	v_bfe_u32 v27, v39, 16, 1
	v_lshrrev_b32_e32 v2, 16, v2
	v_add3_u32 v27, v39, v27, s52
	v_and_or_b32 v27, v27, s53, v2
	v_bfe_u32 v2, v41, 16, 1
	v_add3_u32 v2, v41, v2, s52
	v_bfe_u32 v28, v43, 16, 1
	v_lshrrev_b32_e32 v2, 16, v2
	v_add3_u32 v28, v43, v28, s52
	v_and_or_b32 v28, v28, s53, v2
	v_bfe_u32 v2, v45, 16, 1
	v_add3_u32 v2, v45, v2, s52
	v_bfe_u32 v29, v47, 16, 1
	v_lshrrev_b32_e32 v2, 16, v2
	v_add3_u32 v29, v47, v29, s52
	v_and_or_b32 v29, v29, s53, v2
	v_or_b32_e32 v2, s14, v16
	v_lshlrev_b32_e32 v2, 13, v2
	ds_read2_b32 v[30:31], v15 offset0:16 offset1:24
	v_lshl_add_u64 v[34:35], v[32:33], 0, v[2:3]
	global_store_dwordx4 v[34:35], v[26:29], off
	ds_read2_b32 v[34:35], v15 offset0:49 offset1:57
	ds_read2_b32 v[36:37], v15 offset0:82 offset1:90
	ds_read2_b32 v[38:39], v15 offset0:115 offset1:123
	s_waitcnt lgkmcnt(3)
	v_bfe_u32 v2, v30, 16, 1
	v_add3_u32 v2, v30, v2, s52
	s_waitcnt lgkmcnt(2)
	v_bfe_u32 v26, v34, 16, 1
	ds_read2_b32 v[40:41], v15 offset0:148 offset1:156
	v_lshrrev_b32_e32 v2, 16, v2
	v_add3_u32 v26, v34, v26, s52
	ds_read2_b32 v[42:43], v15 offset0:181 offset1:189
	v_and_or_b32 v26, v26, s53, v2
	s_waitcnt lgkmcnt(3)
	v_bfe_u32 v2, v36, 16, 1
	v_add3_u32 v2, v36, v2, s52
	s_waitcnt lgkmcnt(2)
	v_bfe_u32 v27, v38, 16, 1
	ds_read2_b32 v[44:45], v15 offset0:214 offset1:222
	v_lshrrev_b32_e32 v2, 16, v2
	v_add3_u32 v27, v38, v27, s52
	ds_read2_b32 v[46:47], v15 offset0:247 offset1:255
	v_and_or_b32 v27, v27, s53, v2
	s_waitcnt lgkmcnt(3)
	v_bfe_u32 v2, v40, 16, 1
	v_add3_u32 v2, v40, v2, s52
	s_waitcnt lgkmcnt(2)
	v_bfe_u32 v28, v42, 16, 1
	v_lshrrev_b32_e32 v2, 16, v2
	v_add3_u32 v28, v42, v28, s52
	v_and_or_b32 v28, v28, s53, v2
	s_waitcnt lgkmcnt(1)
	v_bfe_u32 v2, v44, 16, 1
	v_add3_u32 v2, v44, v2, s52
	s_waitcnt lgkmcnt(0)
	v_bfe_u32 v29, v46, 16, 1
	v_lshrrev_b32_e32 v2, 16, v2
	v_add3_u32 v29, v46, v29, s52
	v_and_or_b32 v29, v29, s53, v2
	v_or_b32_e32 v2, s14, v17
	v_lshlrev_b32_e32 v2, 13, v2
	v_lshl_add_u64 v[48:49], v[32:33], 0, v[2:3]
	v_bfe_u32 v2, v31, 16, 1
	global_store_dwordx4 v[48:49], v[26:29], off
	v_add3_u32 v2, v31, v2, s52
	v_lshrrev_b32_e32 v2, 16, v2
	v_bfe_u32 v26, v35, 16, 1
	v_add3_u32 v26, v35, v26, s52
	v_and_or_b32 v26, v26, s53, v2
	v_bfe_u32 v2, v37, 16, 1
	v_add3_u32 v2, v37, v2, s52
	v_bfe_u32 v27, v39, 16, 1
	v_lshrrev_b32_e32 v2, 16, v2
	v_add3_u32 v27, v39, v27, s52
	v_and_or_b32 v27, v27, s53, v2
	v_bfe_u32 v2, v41, 16, 1
	v_add3_u32 v2, v41, v2, s52
	v_bfe_u32 v28, v43, 16, 1
	v_lshrrev_b32_e32 v2, 16, v2
	v_add3_u32 v28, v43, v28, s52
	v_and_or_b32 v28, v28, s53, v2
	v_bfe_u32 v2, v45, 16, 1
	v_add3_u32 v2, v45, v2, s52
	v_bfe_u32 v29, v47, 16, 1
	v_lshrrev_b32_e32 v2, 16, v2
	v_add3_u32 v29, v47, v29, s52
	v_and_or_b32 v29, v29, s53, v2
	v_or_b32_e32 v2, s14, v18
	v_lshlrev_b32_e32 v2, 13, v2
	v_lshl_add_u64 v[30:31], v[32:33], 0, v[2:3]
	global_store_dwordx4 v[30:31], v[26:29], off
	s_waitcnt lgkmcnt(0)
	s_mov_b64 s[14:15], 0
.LBB0_966:
	s_andn2_b64 vcc, exec, s[14:15]
	s_cbranch_vccnz .LBB0_968
	s_add_i32 s8, s3, 0xfffffe00
	s_lshr_b32 s8, s8, 1
	s_and_b32 s8, s8, 0x7fffffc0
	s_and_b32 s14, s4, 0xfe0
	v_or_b32_e32 v2, s8, v12
	v_or_b32_e32 v28, s14, v1
	v_lshlrev_b64 v[26:27], 14, v[2:3]
	v_lshl_add_u64 v[26:27], s[12:13], 0, v[26:27]
	v_lshlrev_b32_e32 v2, 2, v28
	v_lshl_add_u64 v[26:27], v[26:27], 0, v[2:3]
	v_add_co_u32_e32 v28, vcc, 0x8000, v26
	s_nop 1
	v_addc_co_u32_e32 v29, vcc, 0, v27, vcc
	v_add_co_u32_e32 v30, vcc, 0x10000, v26
	s_nop 1
	v_addc_co_u32_e32 v31, vcc, 0, v27, vcc
	v_add_co_u32_e32 v32, vcc, 0x18000, v26
	s_nop 1
	v_addc_co_u32_e32 v33, vcc, 0, v27, vcc
	v_add_co_u32_e32 v34, vcc, 0x20000, v26
	s_nop 1
	v_addc_co_u32_e32 v35, vcc, 0, v27, vcc
	v_add_co_u32_e32 v36, vcc, 0x28000, v26
	s_nop 1
	v_addc_co_u32_e32 v37, vcc, 0, v27, vcc
	v_add_co_u32_e32 v38, vcc, 0x30000, v26
	s_nop 1
	v_addc_co_u32_e32 v39, vcc, 0, v27, vcc
	v_add_co_u32_e32 v40, vcc, 0x38000, v26
	s_nop 1
	v_addc_co_u32_e32 v41, vcc, 0, v27, vcc
	global_load_dword v2, v[26:27], off nt
	global_load_dword v44, v[28:29], off nt
	global_load_dword v45, v[30:31], off nt
	global_load_dword v46, v[32:33], off nt
	global_load_dword v47, v[34:35], off nt
	global_load_dword v48, v[36:37], off nt
	global_load_dword v49, v[38:39], off nt
	global_load_dword v50, v[40:41], off nt
	v_add_co_u32_e32 v28, vcc, 0x40000, v26
	s_nop 1
	v_addc_co_u32_e32 v29, vcc, 0, v27, vcc
	v_add_co_u32_e32 v30, vcc, 0x48000, v26
	s_nop 1
	v_addc_co_u32_e32 v31, vcc, 0, v27, vcc
	v_add_co_u32_e32 v32, vcc, 0x50000, v26
	s_nop 1
	v_addc_co_u32_e32 v33, vcc, 0, v27, vcc
	v_add_co_u32_e32 v34, vcc, 0x58000, v26
	s_nop 1
	v_addc_co_u32_e32 v35, vcc, 0, v27, vcc
	v_add_co_u32_e32 v36, vcc, 0x60000, v26
	s_nop 1
	v_addc_co_u32_e32 v37, vcc, 0, v27, vcc
	v_add_co_u32_e32 v38, vcc, 0x68000, v26
	s_nop 1
	v_addc_co_u32_e32 v39, vcc, 0, v27, vcc
	v_add_co_u32_e32 v40, vcc, 0x70000, v26
	s_nop 1
	v_addc_co_u32_e32 v41, vcc, 0, v27, vcc
	v_add_co_u32_e32 v42, vcc, 0x78000, v26
	s_nop 1
	v_addc_co_u32_e32 v43, vcc, 0, v27, vcc
	global_load_dword v51, v[28:29], off nt
	global_load_dword v52, v[30:31], off nt
	global_load_dword v53, v[32:33], off nt
	global_load_dword v54, v[34:35], off nt
	global_load_dword v55, v[36:37], off nt
	global_load_dword v56, v[38:39], off nt
	global_load_dword v57, v[40:41], off nt
	global_load_dword v58, v[42:43], off nt
	v_add_co_u32_e32 v28, vcc, 0x80000, v26
	s_nop 1
	v_addc_co_u32_e32 v29, vcc, 0, v27, vcc
	v_add_co_u32_e32 v30, vcc, 0x88000, v26
	s_nop 1
	v_addc_co_u32_e32 v31, vcc, 0, v27, vcc
	v_add_co_u32_e32 v32, vcc, 0x90000, v26
	s_nop 1
	v_addc_co_u32_e32 v33, vcc, 0, v27, vcc
	v_add_co_u32_e32 v34, vcc, 0x98000, v26
	s_nop 1
	v_addc_co_u32_e32 v35, vcc, 0, v27, vcc
	v_add_co_u32_e32 v36, vcc, 0xa0000, v26
	s_nop 1
	v_addc_co_u32_e32 v37, vcc, 0, v27, vcc
	v_add_co_u32_e32 v38, vcc, 0xa8000, v26
	s_nop 1
	v_addc_co_u32_e32 v39, vcc, 0, v27, vcc
	v_add_co_u32_e32 v40, vcc, 0xb0000, v26
	s_nop 1
	v_addc_co_u32_e32 v41, vcc, 0, v27, vcc
	v_add_co_u32_e32 v42, vcc, 0xb8000, v26
	s_nop 1
	v_addc_co_u32_e32 v43, vcc, 0, v27, vcc
	global_load_dword v59, v[28:29], off nt
	global_load_dword v60, v[30:31], off nt
	global_load_dword v61, v[32:33], off nt
	global_load_dword v62, v[34:35], off nt
	global_load_dword v63, v[36:37], off nt
	global_load_dword v64, v[38:39], off nt
	global_load_dword v65, v[40:41], off nt
	s_nop 0
	global_load_dword v42, v[42:43], off nt
	v_add_co_u32_e32 v28, vcc, 0xc0000, v26
	s_nop 1
	v_addc_co_u32_e32 v29, vcc, 0, v27, vcc
	v_add_co_u32_e32 v30, vcc, 0xc8000, v26
	s_nop 1
	v_addc_co_u32_e32 v31, vcc, 0, v27, vcc
	v_add_co_u32_e32 v32, vcc, 0xd0000, v26
	s_nop 1
	v_addc_co_u32_e32 v33, vcc, 0, v27, vcc
	v_add_co_u32_e32 v34, vcc, 0xd8000, v26
	s_nop 1
	v_addc_co_u32_e32 v35, vcc, 0, v27, vcc
	v_add_co_u32_e32 v36, vcc, 0xe0000, v26
	s_nop 1
	v_addc_co_u32_e32 v37, vcc, 0, v27, vcc
	v_add_co_u32_e32 v38, vcc, 0xe8000, v26
	s_nop 1
	v_addc_co_u32_e32 v39, vcc, 0, v27, vcc
	v_add_co_u32_e32 v40, vcc, 0xf0000, v26
	s_nop 1
	v_addc_co_u32_e32 v41, vcc, 0, v27, vcc
	v_add_co_u32_e32 v26, vcc, 0xf8000, v26
	s_nop 1
	v_addc_co_u32_e32 v27, vcc, 0, v27, vcc
	global_load_dword v43, v[28:29], off nt
	global_load_dword v66, v[30:31], off nt
	global_load_dword v67, v[32:33], off nt
	s_nop 0
	global_load_dword v34, v[34:35], off nt
	s_nop 0
	global_load_dword v35, v[36:37], off nt
	s_nop 0
	global_load_dword v36, v[38:39], off nt
	global_load_dword v37, v[40:41], off nt
	s_nop 0
	global_load_dword v38, v[26:27], off nt
	v_lshl_add_u64 v[30:31], s[8:9], 2, v[6:7]
	global_load_dwordx4 v[26:29], v[30:31], off
	s_nop 0
	global_load_dwordx4 v[30:33], v[30:31], off offset:16
	s_waitcnt vmcnt(32)
	ds_write2_b32 v13, v2, v44 offset1:66
	s_waitcnt vmcnt(30)
	ds_write2_b32 v13, v45, v46 offset0:132 offset1:198
	s_waitcnt vmcnt(28)
	ds_write2_b32 v19, v47, v48 offset0:8 offset1:74
	s_waitcnt vmcnt(26)
	ds_write2_b32 v19, v49, v50 offset0:140 offset1:206
	s_waitcnt vmcnt(24)
	ds_write2_b32 v20, v51, v52 offset0:16 offset1:82
	s_waitcnt vmcnt(22)
	ds_write2_b32 v20, v53, v54 offset0:148 offset1:214
	s_waitcnt vmcnt(20)
	ds_write2_b32 v21, v55, v56 offset0:24 offset1:90
	s_waitcnt vmcnt(18)
	ds_write2_b32 v21, v57, v58 offset0:156 offset1:222
	s_waitcnt vmcnt(16)
	ds_write2_b32 v22, v59, v60 offset0:32 offset1:98
	s_waitcnt vmcnt(14)
	ds_write2_b32 v22, v61, v62 offset0:164 offset1:230
	s_waitcnt vmcnt(12)
	ds_write2_b32 v23, v63, v64 offset0:40 offset1:106
	s_waitcnt vmcnt(10)
	ds_write2_b32 v23, v65, v42 offset0:172 offset1:238
	s_waitcnt vmcnt(8)
	ds_write2_b32 v24, v43, v66 offset0:48 offset1:114
	s_waitcnt vmcnt(6)
	ds_write2_b32 v24, v67, v34 offset0:180 offset1:246
	s_waitcnt vmcnt(4)
	ds_write2_b32 v25, v35, v36 offset0:56 offset1:122
	s_waitcnt vmcnt(2)
	ds_write2_b32 v25, v37, v38 offset0:188 offset1:254
	s_waitcnt lgkmcnt(0)
	ds_read2_b32 v[40:41], v15 offset0:33 offset1:41
	ds_read2_b32 v[42:43], v15 offset1:8
	ds_read2_b32 v[44:45], v15 offset0:66 offset1:74
	ds_read2_b32 v[46:47], v15 offset0:99 offset1:107
	ds_read2_b32 v[50:51], v15 offset0:132 offset1:140
	ds_read2_b32 v[52:53], v15 offset0:165 offset1:173
	ds_read2_b32 v[54:55], v15 offset0:198 offset1:206
	ds_read2_b32 v[56:57], v15 offset0:231 offset1:239
	s_waitcnt vmcnt(1)
	v_mov_b32_e32 v48, v26
	v_mov_b32_e32 v49, v28
	v_mov_b32_e32 v28, v27
	s_waitcnt lgkmcnt(7)
	v_mov_b32_e32 v26, v40
	s_waitcnt lgkmcnt(4)
	v_mov_b32_e32 v27, v46
	s_waitcnt vmcnt(0)
	v_mov_b32_e32 v58, v30
	v_mov_b32_e32 v59, v32
	v_mov_b32_e32 v32, v31
	s_waitcnt lgkmcnt(2)
	v_mov_b32_e32 v30, v52
	s_waitcnt lgkmcnt(0)
	v_mov_b32_e32 v31, v56
	v_mov_b32_e32 v34, v42
	v_mov_b32_e32 v35, v44
	v_pk_mul_f32 v[26:27], v[28:29], v[26:27]
	v_mov_b32_e32 v36, v50
	v_mov_b32_e32 v37, v54
	v_pk_mul_f32 v[30:31], v[32:33], v[30:31]
	v_pk_mul_f32 v[34:35], v[48:49], v[34:35]
	v_pk_mul_f32 v[36:37], v[58:59], v[36:37]
	v_bfe_u32 v40, v30, 16, 1
	v_bfe_u32 v42, v27, 16, 1
	v_bfe_u32 v44, v26, 16, 1
	v_bfe_u32 v2, v31, 16, 1
	v_add3_u32 v26, v26, v44, s52
	v_add3_u32 v27, v27, v42, s52
	v_add3_u32 v30, v30, v40, s52
	v_bfe_u32 v40, v35, 16, 1
	v_bfe_u32 v42, v36, 16, 1
	v_bfe_u32 v44, v37, 16, 1
	v_add3_u32 v2, v31, v2, s52
	v_bfe_u32 v31, v34, 16, 1
	v_add3_u32 v37, v37, v44, s52
	v_add3_u32 v36, v36, v42, s52
	v_add3_u32 v35, v35, v40, s52
	v_add3_u32 v31, v34, v31, s52
	v_lshrrev_b32_e32 v34, 16, v35
	v_lshrrev_b32_e32 v35, 16, v36
	v_lshrrev_b32_e32 v36, 16, v37
	s_lshl_b32 s8, s8, 1
	v_and_or_b32 v37, v2, s53, v36
	v_or_b32_e32 v2, s14, v14
	v_lshl_add_u64 v[38:39], v[8:9], 0, s[8:9]
	v_lshrrev_b32_e32 v31, 16, v31
	v_lshlrev_b32_e32 v2, 11, v2
	v_mov_b32_e32 v46, v41
	v_and_or_b32 v36, v30, s53, v35
	v_and_or_b32 v35, v27, s53, v34
	v_and_or_b32 v34, v26, s53, v31
	v_lshl_add_u64 v[26:27], v[38:39], 0, v[2:3]
	v_pk_mul_f32 v[30:31], v[28:29], v[46:47]
	v_mov_b32_e32 v54, v51
	global_store_dwordx4 v[26:27], v[34:37], off
	v_mov_b32_e32 v56, v53
	v_bfe_u32 v42, v30, 16, 1
	v_pk_mul_f32 v[34:35], v[58:59], v[54:55]
	v_mov_b32_e32 v44, v43
	v_pk_mul_f32 v[36:37], v[32:33], v[56:57]
	v_add3_u32 v30, v30, v42, s52
	v_bfe_u32 v42, v35, 16, 1
	v_pk_mul_f32 v[26:27], v[48:49], v[44:45]
	v_bfe_u32 v2, v37, 16, 1
	v_bfe_u32 v40, v36, 16, 1
	v_bfe_u32 v41, v31, 16, 1
	v_add3_u32 v35, v35, v42, s52
	v_add3_u32 v31, v31, v41, s52
	v_add3_u32 v36, v36, v40, s52
	v_add3_u32 v2, v37, v2, s52
	v_bfe_u32 v37, v26, 16, 1
	v_bfe_u32 v40, v27, 16, 1
	v_bfe_u32 v41, v34, 16, 1
	v_lshrrev_b32_e32 v35, 16, v35
	v_add3_u32 v34, v34, v41, s52
	v_add3_u32 v27, v27, v40, s52
	v_add3_u32 v26, v26, v37, s52
	v_and_or_b32 v37, v2, s53, v35
	v_or_b32_e32 v2, s14, v16
	v_lshrrev_b32_e32 v26, 16, v26
	v_lshrrev_b32_e32 v27, 16, v27
	v_lshrrev_b32_e32 v34, 16, v34
	v_lshlrev_b32_e32 v2, 11, v2
	v_and_or_b32 v36, v36, s53, v34
	v_and_or_b32 v35, v31, s53, v27
	v_and_or_b32 v34, v30, s53, v26
	v_lshl_add_u64 v[26:27], v[38:39], 0, v[2:3]
	ds_read2_b32 v[30:31], v15 offset0:16 offset1:24
	ds_read2_b32 v[40:41], v15 offset0:82 offset1:90
	global_store_dwordx4 v[26:27], v[34:37], off
	ds_read2_b32 v[26:27], v15 offset0:49 offset1:57
	ds_read2_b32 v[42:43], v15 offset0:115 offset1:123
	ds_read2_b32 v[44:45], v15 offset0:148 offset1:156
	ds_read2_b32 v[46:47], v15 offset0:214 offset1:222
	ds_read2_b32 v[50:51], v15 offset0:181 offset1:189
	ds_read2_b32 v[52:53], v15 offset0:247 offset1:255
	s_waitcnt lgkmcnt(7)
	v_mov_b32_e32 v34, v30
	s_waitcnt lgkmcnt(5)
	v_mov_b32_e32 v36, v26
	s_waitcnt lgkmcnt(4)
	v_mov_b32_e32 v37, v42
	s_waitcnt lgkmcnt(3)
	v_mov_b32_e32 v54, v44
	s_waitcnt lgkmcnt(2)
	v_mov_b32_e32 v55, v46
	v_mov_b32_e32 v35, v40
	v_pk_mul_f32 v[36:37], v[28:29], v[36:37]
	v_pk_mul_f32 v[54:55], v[58:59], v[54:55]
	s_waitcnt lgkmcnt(1)
	v_mov_b32_e32 v56, v50
	s_waitcnt lgkmcnt(0)
	v_mov_b32_e32 v57, v52
	v_pk_mul_f32 v[34:35], v[48:49], v[34:35]
	v_pk_mul_f32 v[56:57], v[32:33], v[56:57]
	v_bfe_u32 v30, v37, 16, 1
	v_bfe_u32 v44, v55, 16, 1
	v_bfe_u32 v2, v57, 16, 1
	v_bfe_u32 v40, v36, 16, 1
	v_add3_u32 v30, v37, v30, s52
	v_bfe_u32 v37, v35, 16, 1
	v_add3_u32 v44, v55, v44, s52
	v_add3_u32 v40, v36, v40, s52
	v_add3_u32 v2, v57, v2, s52
	v_bfe_u32 v36, v34, 16, 1
	v_bfe_u32 v42, v54, 16, 1
	v_add3_u32 v35, v35, v37, s52
	v_lshrrev_b32_e32 v37, 16, v44
	v_bfe_u32 v26, v56, 16, 1
	v_add3_u32 v42, v54, v42, s52
	v_add3_u32 v34, v34, v36, s52
	v_and_or_b32 v37, v2, s53, v37
	v_or_b32_e32 v2, s14, v17
	v_add3_u32 v26, v56, v26, s52
	v_lshrrev_b32_e32 v34, 16, v34
	v_lshrrev_b32_e32 v35, 16, v35
	v_lshrrev_b32_e32 v36, 16, v42
	v_lshlrev_b32_e32 v2, 11, v2
	v_mov_b32_e32 v42, v27
	v_and_or_b32 v36, v26, s53, v36
	v_and_or_b32 v35, v30, s53, v35
	v_and_or_b32 v34, v40, s53, v34
	v_lshl_add_u64 v[54:55], v[38:39], 0, v[2:3]
	v_pk_mul_f32 v[26:27], v[28:29], v[42:43]
	v_mov_b32_e32 v46, v45
	global_store_dwordx4 v[54:55], v[34:37], off
	v_pk_mul_f32 v[28:29], v[58:59], v[46:47]
	v_mov_b32_e32 v52, v51
	v_bfe_u32 v36, v26, 16, 1
	v_mov_b32_e32 v40, v31
	v_pk_mul_f32 v[32:33], v[32:33], v[52:53]
	v_add3_u32 v26, v26, v36, s52
	v_bfe_u32 v36, v29, 16, 1
	v_pk_mul_f32 v[30:31], v[48:49], v[40:41]
	v_bfe_u32 v2, v33, 16, 1
	v_bfe_u32 v34, v32, 16, 1
	v_bfe_u32 v35, v27, 16, 1
	v_add3_u32 v29, v29, v36, s52
	v_add3_u32 v27, v27, v35, s52
	v_add3_u32 v32, v32, v34, s52
	v_add3_u32 v2, v33, v2, s52
	v_bfe_u32 v33, v30, 16, 1
	v_bfe_u32 v34, v31, 16, 1
	v_bfe_u32 v35, v28, 16, 1
	v_lshrrev_b32_e32 v29, 16, v29
	v_add3_u32 v28, v28, v35, s52
	v_add3_u32 v31, v31, v34, s52
	v_add3_u32 v30, v30, v33, s52
	v_and_or_b32 v29, v2, s53, v29
	v_or_b32_e32 v2, s14, v18
	v_lshrrev_b32_e32 v30, 16, v30
	v_lshrrev_b32_e32 v31, 16, v31
	v_lshrrev_b32_e32 v28, 16, v28
	v_lshlrev_b32_e32 v2, 11, v2
	v_and_or_b32 v28, v32, s53, v28
	v_and_or_b32 v27, v27, s53, v31
	v_and_or_b32 v26, v26, s53, v30
	v_lshl_add_u64 v[30:31], v[38:39], 0, v[2:3]
	global_store_dwordx4 v[30:31], v[26:29], off
	s_waitcnt lgkmcnt(0)

.LBB0_969:
	s_andn2_b64 vcc, exec, s[14:15]
	s_cbranch_vccnz .LBB0_962
	s_ashr_i32 s8, s3, 31
	s_lshr_b32 s8, s8, 27
	s_add_i32 s15, s3, s8
	s_ashr_i32 s8, s15, 5
	s_lshl_b32 s14, s8, 6
	s_lshl_b32 s8, s8, 10
	v_or_b32_e32 v26, s14, v12
	s_sub_i32 s8, s4, s8
	v_ashrrev_i32_e32 v27, 31, v26
	v_add_u32_e32 v2, s8, v1
	v_lshlrev_b64 v[26:27], 12, v[26:27]
	v_lshl_add_u64 v[26:27], s[46:47], 0, v[26:27]
	v_max_i32_e32 v2, 0, v2
	v_lshl_add_u64 v[26:27], v[2:3], 2, v[26:27]
	v_add_co_u32_e32 v28, vcc, s16, v26
	s_andn2_b32 s15, s15, 31
	s_nop 0
	v_addc_co_u32_e32 v29, vcc, 0, v27, vcc
	v_add_co_u32_e32 v30, vcc, s17, v26
	s_sub_i32 s15, s3, s15
	s_nop 0
	v_addc_co_u32_e32 v31, vcc, 0, v27, vcc
	v_add_co_u32_e32 v32, vcc, s18, v26
	s_cmp_lt_i32 s15, 0
	s_nop 0
	v_addc_co_u32_e32 v33, vcc, 0, v27, vcc
	v_add_co_u32_e32 v34, vcc, s19, v26
	s_cselect_b64 s[54:55], -1, 0
	s_nop 0
	v_addc_co_u32_e32 v35, vcc, 0, v27, vcc
	v_add_co_u32_e32 v36, vcc, s20, v26
	s_ashr_i32 s15, s14, 31
	s_nop 0
	v_addc_co_u32_e32 v37, vcc, 0, v27, vcc
	v_add_co_u32_e32 v38, vcc, s21, v26
	s_nop 1
	v_addc_co_u32_e32 v39, vcc, 0, v27, vcc
	v_add_co_u32_e32 v40, vcc, s24, v26
	s_nop 1
	v_addc_co_u32_e32 v41, vcc, 0, v27, vcc
	global_load_dword v2, v[26:27], off nt
	global_load_dword v44, v[28:29], off nt
	global_load_dword v45, v[30:31], off nt
	global_load_dword v46, v[32:33], off nt
	global_load_dword v47, v[34:35], off nt
	global_load_dword v48, v[36:37], off nt
	global_load_dword v49, v[38:39], off nt
	global_load_dword v50, v[40:41], off nt
	v_add_co_u32_e32 v28, vcc, s25, v26
	s_nop 1
	v_addc_co_u32_e32 v29, vcc, 0, v27, vcc
	v_add_co_u32_e32 v30, vcc, s26, v26
	s_nop 1
	v_addc_co_u32_e32 v31, vcc, 0, v27, vcc
	v_add_co_u32_e32 v32, vcc, s27, v26
	s_nop 1
	v_addc_co_u32_e32 v33, vcc, 0, v27, vcc
	v_add_co_u32_e32 v34, vcc, s28, v26
	s_nop 1
	v_addc_co_u32_e32 v35, vcc, 0, v27, vcc
	v_add_co_u32_e32 v36, vcc, s29, v26
	s_nop 1
	v_addc_co_u32_e32 v37, vcc, 0, v27, vcc
	v_add_co_u32_e32 v38, vcc, s30, v26
	s_nop 1
	v_addc_co_u32_e32 v39, vcc, 0, v27, vcc
	v_add_co_u32_e32 v40, vcc, s31, v26
	s_nop 1
	v_addc_co_u32_e32 v41, vcc, 0, v27, vcc
	v_add_co_u32_e32 v42, vcc, s33, v26
	s_nop 1
	v_addc_co_u32_e32 v43, vcc, 0, v27, vcc
	global_load_dword v51, v[28:29], off nt
	global_load_dword v52, v[30:31], off nt
	global_load_dword v53, v[32:33], off nt
	global_load_dword v54, v[34:35], off nt
	global_load_dword v55, v[36:37], off nt
	global_load_dword v56, v[38:39], off nt
	global_load_dword v57, v[40:41], off nt
	global_load_dword v58, v[42:43], off nt
	v_add_co_u32_e32 v28, vcc, s34, v26
	s_nop 1
	v_addc_co_u32_e32 v29, vcc, 0, v27, vcc
	v_add_co_u32_e32 v30, vcc, s35, v26
	s_nop 1
	v_addc_co_u32_e32 v31, vcc, 0, v27, vcc
	v_add_co_u32_e32 v32, vcc, s36, v26
	s_nop 1
	v_addc_co_u32_e32 v33, vcc, 0, v27, vcc
	v_add_co_u32_e32 v34, vcc, s37, v26
	s_nop 1
	v_addc_co_u32_e32 v35, vcc, 0, v27, vcc
	v_add_co_u32_e32 v36, vcc, s38, v26
	s_nop 1
	v_addc_co_u32_e32 v37, vcc, 0, v27, vcc
	v_add_co_u32_e32 v38, vcc, s39, v26
	s_nop 1
	v_addc_co_u32_e32 v39, vcc, 0, v27, vcc
	v_add_co_u32_e32 v40, vcc, s40, v26
	s_nop 1
	v_addc_co_u32_e32 v41, vcc, 0, v27, vcc
	v_add_co_u32_e32 v42, vcc, s41, v26
	s_nop 1
	v_addc_co_u32_e32 v43, vcc, 0, v27, vcc
	global_load_dword v59, v[28:29], off nt
	global_load_dword v60, v[30:31], off nt
	global_load_dword v61, v[32:33], off nt
	global_load_dword v62, v[34:35], off nt
	global_load_dword v63, v[36:37], off nt
	global_load_dword v64, v[38:39], off nt
	s_nop 0
	global_load_dword v40, v[40:41], off nt
	s_nop 0
	global_load_dword v41, v[42:43], off nt
	v_add_co_u32_e32 v28, vcc, s42, v26
	s_nop 1
	v_addc_co_u32_e32 v29, vcc, 0, v27, vcc
	v_add_co_u32_e32 v30, vcc, s43, v26
	s_nop 1
	v_addc_co_u32_e32 v31, vcc, 0, v27, vcc
	v_add_co_u32_e32 v32, vcc, s44, v26
	s_nop 1
	v_addc_co_u32_e32 v33, vcc, 0, v27, vcc
	v_add_co_u32_e32 v34, vcc, s45, v26
	s_nop 1
	v_addc_co_u32_e32 v35, vcc, 0, v27, vcc
	v_add_co_u32_e32 v36, vcc, s48, v26
	s_nop 1
	v_addc_co_u32_e32 v37, vcc, 0, v27, vcc
	v_add_co_u32_e32 v38, vcc, s49, v26
	s_nop 1
	v_addc_co_u32_e32 v39, vcc, 0, v27, vcc
	global_load_dword v42, v[28:29], off nt
	s_nop 0
	global_load_dword v30, v[30:31], off nt
	s_nop 0
	global_load_dword v31, v[32:33], off nt
	s_nop 0
	global_load_dword v32, v[34:35], off nt
	global_load_dword v33, v[36:37], off nt
	s_nop 0
	global_load_dword v34, v[38:39], off nt
	v_add_co_u32_e32 v28, vcc, s50, v26
	s_nop 1
	v_addc_co_u32_e32 v29, vcc, 0, v27, vcc
	v_add_co_u32_e32 v26, vcc, s51, v26
	s_nop 1
	v_addc_co_u32_e32 v27, vcc, 0, v27, vcc
	global_load_dword v28, v[28:29], off nt
	s_nop 0
	global_load_dword v26, v[26:27], off nt
	v_cndmask_b32_e64 v27, 1.0, 0, s[54:55]
	s_waitcnt vmcnt(31)
	v_mul_f32_e32 v2, v27, v2
	s_waitcnt vmcnt(30)
	v_mul_f32_e32 v29, v27, v44
	ds_write2_b32 v13, v2, v29 offset1:66
	s_waitcnt vmcnt(29)
	v_mul_f32_e32 v2, v27, v45
	s_waitcnt vmcnt(28)
	v_mul_f32_e32 v29, v27, v46
	ds_write2_b32 v13, v2, v29 offset0:132 offset1:198
	s_waitcnt vmcnt(27)
	v_mul_f32_e32 v2, v27, v47
	s_waitcnt vmcnt(26)
	v_mul_f32_e32 v29, v27, v48
	ds_write2_b32 v19, v2, v29 offset0:8 offset1:74
	s_waitcnt vmcnt(25)
	v_mul_f32_e32 v2, v27, v49
	s_waitcnt vmcnt(24)
	v_mul_f32_e32 v29, v27, v50
	ds_write2_b32 v19, v2, v29 offset0:140 offset1:206
	s_waitcnt vmcnt(23)
	v_mul_f32_e32 v2, v27, v51
	s_waitcnt vmcnt(22)
	v_mul_f32_e32 v29, v27, v52
	ds_write2_b32 v20, v2, v29 offset0:16 offset1:82
	s_waitcnt vmcnt(21)
	v_mul_f32_e32 v2, v27, v53
	s_waitcnt vmcnt(20)
	v_mul_f32_e32 v29, v27, v54
	ds_write2_b32 v20, v2, v29 offset0:148 offset1:214
	s_waitcnt vmcnt(19)
	v_mul_f32_e32 v2, v27, v55
	s_waitcnt vmcnt(18)
	v_mul_f32_e32 v29, v27, v56
	ds_write2_b32 v21, v2, v29 offset0:24 offset1:90
	s_waitcnt vmcnt(17)
	v_mul_f32_e32 v2, v27, v57
	s_waitcnt vmcnt(16)
	v_mul_f32_e32 v29, v27, v58
	ds_write2_b32 v21, v2, v29 offset0:156 offset1:222
	v_add_u32_e32 v48, s8, v14
	v_ashrrev_i32_e32 v49, 31, v48
	v_lshlrev_b64 v[50:51], 11, v[48:49]
	s_waitcnt vmcnt(15)
	v_mul_f32_e32 v2, v27, v59
	s_waitcnt vmcnt(14)
	v_mul_f32_e32 v29, v27, v60
	ds_write2_b32 v22, v2, v29 offset0:32 offset1:98
	s_waitcnt vmcnt(13)
	v_mul_f32_e32 v2, v27, v61
	s_waitcnt vmcnt(12)
	v_mul_f32_e32 v29, v27, v62
	ds_write2_b32 v22, v2, v29 offset0:164 offset1:230
	s_waitcnt vmcnt(11)
	v_mul_f32_e32 v2, v27, v63
	s_waitcnt vmcnt(10)
	v_mul_f32_e32 v29, v27, v64
	ds_write2_b32 v23, v2, v29 offset0:40 offset1:106
	s_waitcnt vmcnt(9)
	v_mul_f32_e32 v2, v27, v40
	s_waitcnt vmcnt(8)
	v_mul_f32_e32 v29, v27, v41
	ds_write2_b32 v23, v2, v29 offset0:172 offset1:238
	s_waitcnt vmcnt(7)
	v_mul_f32_e32 v2, v27, v42
	s_waitcnt vmcnt(6)
	v_mul_f32_e32 v29, v27, v30
	ds_write2_b32 v24, v2, v29 offset0:48 offset1:114
	s_waitcnt vmcnt(5)
	v_mul_f32_e32 v2, v27, v31
	s_waitcnt vmcnt(4)
	v_mul_f32_e32 v29, v27, v32
	ds_write2_b32 v24, v2, v29 offset0:180 offset1:246
	s_waitcnt vmcnt(3)
	v_mul_f32_e32 v2, v27, v33
	s_waitcnt vmcnt(2)
	v_mul_f32_e32 v29, v27, v34
	ds_write2_b32 v25, v2, v29 offset0:56 offset1:122
	v_lshl_add_u64 v[32:33], s[14:15], 1, v[10:11]
	v_lshl_add_u64 v[50:51], v[32:33], 0, v[50:51]
	s_waitcnt vmcnt(1)
	v_mul_f32_e32 v2, v27, v28
	s_waitcnt vmcnt(0)
	v_mul_f32_e32 v26, v27, v26
	ds_write2_b32 v25, v2, v26 offset0:188 offset1:254
	s_waitcnt lgkmcnt(0)
	ds_read2_b32 v[30:31], v15 offset1:8
	ds_read2_b32 v[34:35], v15 offset0:33 offset1:41
	ds_read2_b32 v[36:37], v15 offset0:66 offset1:74
	ds_read2_b32 v[38:39], v15 offset0:99 offset1:107
	ds_read2_b32 v[40:41], v15 offset0:132 offset1:140
	s_waitcnt lgkmcnt(4)
	v_bfe_u32 v2, v30, 16, 1
	v_add3_u32 v2, v30, v2, s52
	s_waitcnt lgkmcnt(3)
	v_bfe_u32 v26, v34, 16, 1
	v_lshrrev_b32_e32 v2, 16, v2
	v_add3_u32 v26, v34, v26, s52
	ds_read2_b32 v[42:43], v15 offset0:165 offset1:173
	v_and_or_b32 v26, v26, s53, v2
	s_waitcnt lgkmcnt(3)
	v_bfe_u32 v2, v36, 16, 1
	v_add3_u32 v2, v36, v2, s52
	s_waitcnt lgkmcnt(2)
	v_bfe_u32 v27, v38, 16, 1
	ds_read2_b32 v[44:45], v15 offset0:198 offset1:206
	v_lshrrev_b32_e32 v2, 16, v2
	v_add3_u32 v27, v38, v27, s52
	ds_read2_b32 v[46:47], v15 offset0:231 offset1:239
	v_and_or_b32 v27, v27, s53, v2
	s_waitcnt lgkmcnt(3)
	v_bfe_u32 v2, v40, 16, 1
	v_add3_u32 v2, v40, v2, s52
	s_waitcnt lgkmcnt(2)
	v_bfe_u32 v28, v42, 16, 1
	v_lshrrev_b32_e32 v2, 16, v2
	v_add3_u32 v28, v42, v28, s52
	v_and_or_b32 v28, v28, s53, v2
	s_waitcnt lgkmcnt(1)
	v_bfe_u32 v2, v44, 16, 1
	v_add3_u32 v2, v44, v2, s52
	s_waitcnt lgkmcnt(0)
	v_bfe_u32 v29, v46, 16, 1
	v_lshrrev_b32_e32 v2, 16, v2
	v_add3_u32 v29, v46, v29, s52
	v_and_or_b32 v29, v29, s53, v2
	v_bfe_u32 v2, v31, 16, 1
	global_store_dwordx4 v[50:51], v[26:29], off
	v_add3_u32 v2, v31, v2, s52
	v_lshrrev_b32_e32 v2, 16, v2
	v_bfe_u32 v26, v35, 16, 1
	v_add3_u32 v26, v35, v26, s52
	v_and_or_b32 v26, v26, s53, v2
	v_bfe_u32 v2, v37, 16, 1
	v_add3_u32 v2, v37, v2, s52
	v_bfe_u32 v27, v39, 16, 1
	v_lshrrev_b32_e32 v2, 16, v2
	v_add3_u32 v27, v39, v27, s52
	v_and_or_b32 v27, v27, s53, v2
	v_bfe_u32 v2, v41, 16, 1
	v_add3_u32 v2, v41, v2, s52
	v_bfe_u32 v28, v43, 16, 1
	v_lshrrev_b32_e32 v2, 16, v2
	v_add3_u32 v28, v43, v28, s52
	v_and_or_b32 v28, v28, s53, v2
	v_bfe_u32 v2, v45, 16, 1
	v_add_u32_e32 v30, 8, v48
	v_add3_u32 v2, v45, v2, s52
	v_bfe_u32 v29, v47, 16, 1
	v_ashrrev_i32_e32 v31, 31, v30
	v_lshrrev_b32_e32 v2, 16, v2
	v_add3_u32 v29, v47, v29, s52
	v_lshlrev_b64 v[30:31], 11, v[30:31]
	v_and_or_b32 v29, v29, s53, v2
	ds_read2_b32 v[34:35], v15 offset0:16 offset1:24
	v_lshl_add_u64 v[30:31], v[32:33], 0, v[30:31]
	global_store_dwordx4 v[30:31], v[26:29], off
	ds_read2_b32 v[30:31], v15 offset0:49 offset1:57
	ds_read2_b32 v[36:37], v15 offset0:82 offset1:90
	ds_read2_b32 v[38:39], v15 offset0:115 offset1:123
	s_waitcnt lgkmcnt(3)
	v_bfe_u32 v2, v34, 16, 1
	v_add3_u32 v2, v34, v2, s52
	s_waitcnt lgkmcnt(2)
	v_bfe_u32 v26, v30, 16, 1
	ds_read2_b32 v[40:41], v15 offset0:148 offset1:156
	v_lshrrev_b32_e32 v2, 16, v2
	v_add3_u32 v26, v30, v26, s52
	ds_read2_b32 v[42:43], v15 offset0:181 offset1:189
	v_and_or_b32 v26, v26, s53, v2
	s_waitcnt lgkmcnt(3)
	v_bfe_u32 v2, v36, 16, 1
	v_add3_u32 v2, v36, v2, s52
	s_waitcnt lgkmcnt(2)
	v_bfe_u32 v27, v38, 16, 1
	ds_read2_b32 v[44:45], v15 offset0:214 offset1:222
	v_lshrrev_b32_e32 v2, 16, v2
	v_add3_u32 v27, v38, v27, s52
	ds_read2_b32 v[46:47], v15 offset0:247 offset1:255
	v_and_or_b32 v27, v27, s53, v2
	s_waitcnt lgkmcnt(3)
	v_bfe_u32 v2, v40, 16, 1
	v_add3_u32 v2, v40, v2, s52
	s_waitcnt lgkmcnt(2)
	v_bfe_u32 v28, v42, 16, 1
	v_lshrrev_b32_e32 v2, 16, v2
	v_add3_u32 v28, v42, v28, s52
	v_and_or_b32 v28, v28, s53, v2
	s_waitcnt lgkmcnt(1)
	v_bfe_u32 v2, v44, 16, 1
	v_add_u32_e32 v50, 16, v48
	v_add3_u32 v2, v44, v2, s52
	s_waitcnt lgkmcnt(0)
	v_bfe_u32 v29, v46, 16, 1
	v_ashrrev_i32_e32 v51, 31, v50
	v_lshrrev_b32_e32 v2, 16, v2
	v_add3_u32 v29, v46, v29, s52
	v_lshlrev_b64 v[50:51], 11, v[50:51]
	v_and_or_b32 v29, v29, s53, v2
	v_lshl_add_u64 v[50:51], v[32:33], 0, v[50:51]
	v_bfe_u32 v2, v35, 16, 1
	global_store_dwordx4 v[50:51], v[26:29], off
	v_add3_u32 v2, v35, v2, s52
	v_lshrrev_b32_e32 v2, 16, v2
	v_bfe_u32 v26, v31, 16, 1
	v_add3_u32 v26, v31, v26, s52
	v_and_or_b32 v26, v26, s53, v2
	v_bfe_u32 v2, v37, 16, 1
	v_add3_u32 v2, v37, v2, s52
	v_bfe_u32 v27, v39, 16, 1
	v_lshrrev_b32_e32 v2, 16, v2
	v_add3_u32 v27, v39, v27, s52
	v_and_or_b32 v27, v27, s53, v2
	v_bfe_u32 v2, v41, 16, 1
	v_add3_u32 v2, v41, v2, s52
	v_bfe_u32 v28, v43, 16, 1
	v_lshrrev_b32_e32 v2, 16, v2
	v_add3_u32 v28, v43, v28, s52
	v_and_or_b32 v28, v28, s53, v2
	v_bfe_u32 v2, v45, 16, 1
	v_add_u32_e32 v30, 24, v48
	v_add3_u32 v2, v45, v2, s52
	v_bfe_u32 v29, v47, 16, 1
	v_ashrrev_i32_e32 v31, 31, v30
	v_lshrrev_b32_e32 v2, 16, v2
	v_add3_u32 v29, v47, v29, s52
	v_lshlrev_b64 v[30:31], 11, v[30:31]
	v_and_or_b32 v29, v29, s53, v2
	v_lshl_add_u64 v[30:31], v[32:33], 0, v[30:31]
	global_store_dwordx4 v[30:31], v[26:29], off
	s_waitcnt lgkmcnt(0)
	s_branch .LBB0_962

.LBB0_998:
	v_lshl_add_u32 v158, s8, 8, v1
	v_ashrrev_i32_e32 v159, 31, v158
	v_lshl_add_u64 v[130:131], v[158:159], 2, s[16:17]
	global_load_dword v132, v[130:131], off nt
	global_load_dword v179, v[130:131], off offset:64 nt
	global_load_dword v178, v[130:131], off offset:128 nt
	global_load_dword v177, v[130:131], off offset:192 nt
	global_load_dword v176, v[130:131], off offset:512 nt
	global_load_dword v175, v[130:131], off offset:576 nt
	global_load_dword v174, v[130:131], off offset:640 nt
	global_load_dword v173, v[130:131], off offset:704 nt
	v_mad_i64_i32 v[160:161], s[42:43], v158, s67, 0
	s_mov_b64 s[44:45], -1
	s_mov_b64 s[8:9], 0
	s_cmp_lt_i32 s10, 1
	s_mov_b64 s[42:43], 0
	s_waitcnt vmcnt(0)
	v_fmamk_f32 v130, v132, 0x3a800000, v171
	v_mul_f32_e32 v131, 0x4b800000, v130
	v_cmp_gt_f32_e32 vcc, s66, v130
	s_nop 1
	v_cndmask_b32_e32 v130, v130, v131, vcc
	v_rsq_f32_e32 v142, v130
	s_nop 0
	v_mul_f32_e32 v162, 0x45800000, v142
	v_cndmask_b32_e32 v162, v142, v162, vcc
	v_pk_mul_f32 v[128:129], v[128:129], v[162:163] op_sel_hi:[1,0]
	v_pk_mul_f32 v[164:165], v[126:127], v[162:163] op_sel_hi:[1,0]
	v_pk_mul_f32 v[124:125], v[124:125], v[162:163] op_sel_hi:[1,0]
	v_pk_mul_f32 v[126:127], v[122:123], v[162:163] op_sel_hi:[1,0]
	s_cbranch_scc0 .LBB0_1097
	s_and_b64 vcc, exec, s[44:45]
	s_cbranch_vccnz .LBB0_1100
